# all epilogue-entry DMA drains (dispatch, SwiGLU, UQKA, RGG, VT) relaxed so next-unit tile loads stay in flight; on top of the FFO y_old touch stack
# speedup vs baseline: 1.0025x; 1.0017x over previous
.LBB0_892:
	s_and_b64 vcc, exec, s[6:7]
	s_cbranch_vccz .LBB0_965
	v_readlane_b32 s10, v255, 18
	s_add_u32 s6, s12, 0x27900000
	s_addc_u32 s7, s13, 0
	v_add_u32_e32 v5, s10, v189
	v_lshl_add_u32 v2, v5, 3, 0
	v_add_u32_e32 v4, 0x20000, v2
	ds_read2_b64 v[176:179], v4 offset1:16
	s_add_u32 s8, s12, 0x33f00000
	v_lshlrev_b32_e32 v210, 3, v191
	s_addc_u32 s9, s13, 0
	v_add_u32_e32 v180, s70, v210
	s_waitcnt lgkmcnt(0)
	v_mul_f32_e32 v2, 0x3a000000, v176
	s_and_b32 s10, s3, -4
	s_nop 0
	v_mul_f32_e32 v134, v2, v2
	s_cmp_eq_u32 s10, 4
	v_fma_f32 v134, v177, s72, -v134
	ds_read2_b64 v[174:177], v4 offset0:32 offset1:48
	ds_read2_b64 v[170:173], v4 offset0:128 offset1:144
	ds_read2_b64 v[162:165], v4 offset0:160 offset1:176
	v_lshlrev_b32_e32 v4, 2, v180
	v_readlane_b32 s10, v254, 42
	v_readlane_b32 s11, v254, 43
	v_add_f32_e32 v134, 0x3727c5ac, v134
	v_add_u32_e32 v138, s10, v4
	v_add_u32_e32 v142, s11, v4
	v_or_b32_e32 v4, 16, v4
	v_rsq_f32_e32 v208, v134
	v_add_u32_e32 v134, s10, v4
	v_add_u32_e32 v4, s11, v4
	ds_read_b128 v[154:157], v134
	ds_read_b128 v[150:153], v4
	ds_read_b128 v[166:169], v138
	ds_read_b128 v[134:137], v138 offset:512
	ds_read_b128 v[158:161], v142
	ds_read_b128 v[146:149], v138 offset:528
	ds_read_b128 v[138:141], v142 offset:512
	ds_read_b128 v[142:145], v142 offset:528
	v_lshl_add_u32 v4, s3, 8, v180
	s_cselect_b64 vcc, -1, 0
	v_mov_b32_e32 v180, 0x3d800000
	v_readlane_b32 s10, v255, 23
	v_cndmask_b32_e32 v204, 1.0, v180, vcc
	v_cmp_gt_i32_e32 vcc, 2, v191
	v_readlane_b32 s11, v255, 24
	s_and_b64 s[10:11], s[10:11], vcc
	s_and_b32 s18, s84, 1
	v_lshl_add_u32 v206, s4, 8, v5
	v_mov_b32_e32 v205, v204
	v_ashrrev_i32_e32 v211, 31, v210
	s_cmp_eq_u32 s18, 0
	v_ashrrev_i32_e32 v5, 31, v4
	s_cbranch_scc1 .LBB0_900
	s_waitcnt lgkmcnt(5)
	v_pk_fma_f32 v[180:181], v[2:3], v[168:169], v[128:129] op_sel_hi:[0,1,1] neg_lo:[1,0,0] neg_hi:[1,0,0]
	v_pk_fma_f32 v[182:183], v[2:3], v[166:167], v[126:127] op_sel_hi:[0,1,1] neg_lo:[1,0,0] neg_hi:[1,0,0]
	s_waitcnt lgkmcnt(3)
	v_pk_fma_f32 v[180:181], v[208:209], v[180:181], v[160:161] op_sel_hi:[0,1,1]
	v_pk_fma_f32 v[184:185], v[208:209], v[182:183], v[158:159] op_sel_hi:[0,1,1]
	v_mov_b32_e32 v186, v204
	v_mov_b32_e32 v187, v204
	v_pk_mul_f32 v[182:183], v[186:187], v[180:181]
	v_pk_mul_f32 v[180:181], v[204:205], v[184:185]
	v_pk_fma_f32 v[184:185], v[2:3], v[156:157], v[132:133] op_sel_hi:[0,1,1] neg_lo:[1,0,0] neg_hi:[1,0,0]
	v_pk_fma_f32 v[212:213], v[2:3], v[154:155], v[130:131] op_sel_hi:[0,1,1] neg_lo:[1,0,0] neg_hi:[1,0,0]
	v_pk_fma_f32 v[184:185], v[208:209], v[184:185], v[152:153] op_sel_hi:[0,1,1]
	v_pk_fma_f32 v[212:213], v[208:209], v[212:213], v[150:151] op_sel_hi:[0,1,1]
	v_pk_mul_f32 v[186:187], v[186:187], v[184:185]
	v_pk_mul_f32 v[184:185], v[204:205], v[212:213]
	s_cmp_gt_i32 s3, 11
	s_mov_b64 s[16:17], -1
	s_cbranch_scc0 .LBB0_898
	s_and_saveexec_b64 s[16:17], s[10:11]
	s_cbranch_execz .LBB0_897
	v_ashrrev_i32_e32 v207, 31, v206
	v_lshlrev_b64 v[212:213], 6, v[206:207]
	v_lshl_add_u64 v[212:213], s[8:9], 0, v[212:213]
	v_lshl_add_u64 v[212:213], v[210:211], 2, v[212:213]
	global_store_dwordx4 v[212:213], v[180:183], off
	global_store_dwordx4 v[212:213], v[184:187], off offset:16

.LBB0_1172:
	s_andn2_b64 vcc, exec, s[0:1]
	s_cbranch_vccnz .LBB0_1182
	v_lshl_add_u32 v2, v191, 3, s70
	s_waitcnt lgkmcnt(0)
	v_lshlrev_b32_e32 v4, 2, v2
	v_readlane_b32 s8, v254, 42
	v_readlane_b32 s9, v254, 43
	s_or_b32 s0, s37, s36
	v_add_u32_e32 v5, s8, v4
	s_nop 0
	v_add_u32_e32 v134, s9, v4
	v_or_b32_e32 v4, 16, v4
	s_cmp_eq_u32 s0, 0
	ds_read_b128 v[162:165], v5
	ds_read_b128 v[146:149], v5 offset:512
	ds_read_b128 v[158:161], v134
	ds_read_b128 v[142:145], v134 offset:512
	v_add_u32_e32 v5, s8, v4
	v_add_u32_e32 v4, s9, v4
	v_readlane_b32 s8, v255, 18
	s_cselect_b64 s[6:7], -1, 0
	s_add_u32 s0, s12, 0x21600000
	ds_read_b128 v[154:157], v5
	ds_read_b128 v[138:141], v5 offset:512
	ds_read_b128 v[150:153], v4
	ds_read_b128 v[134:137], v4 offset:512
	v_lshl_add_u32 v4, s3, 7, v2
	v_add_u32_e32 v2, s8, v189
	s_addc_u32 s1, s13, 0
	v_lshlrev_b32_e32 v180, 3, v2
	s_add_i32 s8, 0, 0x20000
	v_add_u32_e32 v5, s8, v180
	ds_read2_b64 v[174:177], v5 offset0:16 offset1:32
	ds_read2_b64 v[170:173], v5 offset0:48 offset1:128
	ds_read2_b64 v[166:169], v5 offset0:144 offset1:160
	ds_read_b64 v[178:179], v5 offset:1408
	v_lshl_add_u32 v2, s4, 8, v2
	v_ashrrev_i32_e32 v5, 31, v4
	s_bitcmp0_b32 s84, 0
	s_waitcnt lgkmcnt(11)
	v_xor_b32_e32 v165, 0x80000000, v165
	v_xor_b32_e32 v164, 0x80000000, v164
	s_waitcnt lgkmcnt(7)
	v_xor_b32_e32 v157, 0x80000000, v157
	v_xor_b32_e32 v156, 0x80000000, v156
	s_cbranch_scc0 .LBB0_1441
	s_bitcmp0_b32 s84, 1
	s_cbranch_scc0 .LBB0_1442
